# GQA and NA latent jobs: static s_setprio 1 for waves 4-7 at job entry, per-cluster flips replaced by s_nop 0
# speedup vs baseline: 1.0025x; 1.0025x over previous
; __device__ void mixer_phase(const Params& p, int layer, char* smem) {
;     ...
;       for (int rep = 0; rep < REP_ATT; ++rep) {
;         if (job < 768) attn_job<0>(p, layer, job - 256, smem);
;         else if (job < 1280) attn_job<1>(p, layer, job - 768, smem);
;         else if (job < 1344) attn_job<2>(p, layer, job - 1280, smem);
;         else attn_job<3>(p, layer, job - 1344, smem);
;         __syncthreads();
.LBB0_457:
	v_readfirstlane_b32 s100, v234
	s_nop 0
	s_bitcmp1_b32 s100, 8
	s_cbranch_scc0 .Lprio_skip_na
	s_setprio 1

; DI f32x16 mfma32(bf16x8 a, bf16x8 b, f32x16 c) { return __builtin_amdgcn_mfma_f32_32x32x16_bf16(a, b, c, 0, 0, 0); }
; DI float xmax32(float x) { auto r = __builtin_amdgcn_permlane32_swap(__float_as_uint(x), __float_as_uint(x), false, false); return fmaxf(__uint_as_float(r[0]), __uint_as_float(r[1])); }
; template <int NB>
; DI void softmax_pv(f32x16 (&s)[2], float& mrun, float& lsum, f32x16 (&O)[2], unsigned vaddr) {
;     ...
;   if (NB == 2) tr_read_vtile(vf, vaddr);
;   else tr_read_vtile8(vf8, vaddr);
;   float mx = -1e30f;
; #pragma unroll
;   for (int kb = 0; kb < NB; ++kb)
; #pragma unroll
;     for (int e = 0; e < 16; ++e) mx = fmaxf(mx, s[kb][e]);
;   mx = xmax32(mx);
;   constexpr float THR = 8.f;
;   float alpha = 1.f;
;   if (__builtin_amdgcn_ballot_w64(mx - mrun > THR) != 0ull) {
;     const float mnew = fmaxf(mrun, mx);
;     alpha = __builtin_amdgcn_exp2f((mrun - mnew) * L2E);
;     mrun = mnew;
; #pragma unroll
;     for (int e = 0; e < 16; ++e) { O[0][e] *= alpha; O[1][e] *= alpha; }
; template <int kind>
; __device__ void attn_job(const Params& p, int layer, int idx, char* smem) {
;     ...
;       f32x16 s[2];
;       __builtin_amdgcn_s_setprio(1);
; #pragma unroll
;       for (int kb = 0; kb < 2; ++kb) {
; #pragma unroll
;         for (int st = 0; st < 4; ++st) s[kb] = mfma32(ld_frag16(Kb + (kb * 32 + tq) * KS_STRIDE + 16 * st + 8 * hh), qf[st], st == 0 ? zero16 : s[kb]);
;       }
;       __builtin_amdgcn_s_setprio(0);
;       softmax_pv<2>(s, mrun, lsum, O, (unsigned)(size_t)Vb + vlane_off);
.LBB0_469:
	s_add_i32 s3, s14, 0x4800
	s_cmp_lt_u32 s13, 4
	s_mov_b64 s[0:1], -1
	s_cbranch_scc0 .LBB0_472
	s_nop 0
	v_add3_u32 v0, s14, v180, v188
	ds_read_b128 v[2:5], v0
	ds_read_b128 v[6:9], v0 offset:32
	ds_read_b128 v[10:13], v0 offset:64
	ds_read_b128 v[152:155], v0 offset:96
	ds_read_b128 v[156:159], v0 offset:4608
	ds_read_b128 v[160:163], v0 offset:4640
	ds_read_b128 v[164:167], v0 offset:4672
	ds_read_b128 v[168:171], v0 offset:4704
	s_waitcnt lgkmcnt(7)
	v_mfma_f32_32x32x16_bf16 v[112:127], v[2:5], v[136:139], v[16:31]
	s_waitcnt lgkmcnt(6)
	v_mfma_f32_32x32x16_bf16 v[112:127], v[6:9], v[128:131], v[112:127]
	s_waitcnt lgkmcnt(5)
	v_mfma_f32_32x32x16_bf16 v[112:127], v[10:13], v[132:135], v[112:127]
	s_waitcnt lgkmcnt(4)
	v_mfma_f32_32x32x16_bf16 v[112:127], v[152:155], v[140:143], v[112:127]
	s_waitcnt lgkmcnt(3)
	v_mfma_f32_32x32x16_bf16 v[96:111], v[156:159], v[136:139], v[16:31]
	s_waitcnt lgkmcnt(2)
	v_mfma_f32_32x32x16_bf16 v[96:111], v[160:163], v[128:131], v[96:111]
	s_waitcnt lgkmcnt(1)
	v_mfma_f32_32x32x16_bf16 v[96:111], v[164:167], v[132:135], v[96:111]
	s_waitcnt lgkmcnt(0)
	v_mfma_f32_32x32x16_bf16 v[96:111], v[168:171], v[140:143], v[96:111]
	s_nop 0
	v_add_u32_e32 v0, s3, v181
	ds_read_b64_tr_b16 v[168:169], v0 offset:0
	ds_read_b64_tr_b16 v[170:171], v0 offset:1152
	ds_read_b64_tr_b16 v[164:165], v0 offset:64
	ds_read_b64_tr_b16 v[166:167], v0 offset:1216
	ds_read_b64_tr_b16 v[160:161], v0 offset:2304
	ds_read_b64_tr_b16 v[162:163], v0 offset:3456
	ds_read_b64_tr_b16 v[156:157], v0 offset:2368
	ds_read_b64_tr_b16 v[158:159], v0 offset:3520
	ds_read_b64_tr_b16 v[152:153], v0 offset:4608
	ds_read_b64_tr_b16 v[154:155], v0 offset:5760
	ds_read_b64_tr_b16 v[10:11], v0 offset:4672
	ds_read_b64_tr_b16 v[12:13], v0 offset:5824
	ds_read_b64_tr_b16 v[6:7], v0 offset:6912
	ds_read_b64_tr_b16 v[8:9], v0 offset:8064
	ds_read_b64_tr_b16 v[2:3], v0 offset:6976
	ds_read_b64_tr_b16 v[4:5], v0 offset:8128
	s_waitcnt lgkmcnt(0)
	v_max3_f32 v0, v112, s24, v113
	v_max3_f32 v0, v0, v114, v115
	v_max3_f32 v0, v0, v116, v117
	v_max3_f32 v0, v0, v118, v119
	v_max3_f32 v0, v0, v120, v121
	v_max3_f32 v0, v0, v122, v123
	v_max3_f32 v0, v0, v124, v125
	v_max3_f32 v0, v0, v126, v127
	s_nop 1
	v_max3_f32 v0, v0, v96, v97
	v_max3_f32 v0, v0, v98, v99
	v_max3_f32 v0, v0, v100, v101
	v_max3_f32 v0, v0, v102, v103
	v_max3_f32 v0, v0, v104, v105
	v_max3_f32 v0, v0, v106, v107
	v_max3_f32 v0, v0, v108, v109
	v_max3_f32 v0, v0, v110, v111
	v_mov_b32_e32 v64, v0
	s_nop 1
	v_permlane32_swap_b32_e32 v0, v64
	v_max_f32_e32 v64, v64, v64
	v_max_f32_e32 v0, v0, v0
	v_max_f32_e32 v0, v0, v64
	v_sub_f32_e32 v64, v0, v193
	v_cmp_lt_f32_e32 vcc, s25, v64
	s_cbranch_vccz .LBB0_473
	v_max_f32_e32 v0, v0, v0
	v_max_f32_e32 v64, v193, v193
	v_max_f32_e32 v224, v64, v0
	v_sub_f32_e32 v0, v193, v224
	v_mul_f32_e32 v0, 0x3fb8aa3b, v0
	v_exp_f32_e32 v0, v0
	s_nop 0
	v_pk_mul_f32 v[78:79], v[46:47], v[0:1] op_sel_hi:[1,0]
	v_pk_mul_f32 v[76:77], v[44:45], v[0:1] op_sel_hi:[1,0]
	v_pk_mul_f32 v[74:75], v[42:43], v[0:1] op_sel_hi:[1,0]
	v_pk_mul_f32 v[72:73], v[40:41], v[0:1] op_sel_hi:[1,0]
	v_pk_mul_f32 v[70:71], v[38:39], v[0:1] op_sel_hi:[1,0]
	v_pk_mul_f32 v[68:69], v[36:37], v[0:1] op_sel_hi:[1,0]
	v_pk_mul_f32 v[66:67], v[34:35], v[0:1] op_sel_hi:[1,0]
	v_pk_mul_f32 v[64:65], v[32:33], v[0:1] op_sel_hi:[1,0]
	v_pk_mul_f32 v[94:95], v[62:63], v[0:1] op_sel_hi:[1,0]
	v_pk_mul_f32 v[92:93], v[60:61], v[0:1] op_sel_hi:[1,0]
	v_pk_mul_f32 v[90:91], v[58:59], v[0:1] op_sel_hi:[1,0]
	v_pk_mul_f32 v[88:89], v[56:57], v[0:1] op_sel_hi:[1,0]
	v_pk_mul_f32 v[86:87], v[54:55], v[0:1] op_sel_hi:[1,0]
	v_pk_mul_f32 v[84:85], v[52:53], v[0:1] op_sel_hi:[1,0]
	v_pk_mul_f32 v[82:83], v[50:51], v[0:1] op_sel_hi:[1,0]
	v_pk_mul_f32 v[80:81], v[48:49], v[0:1] op_sel_hi:[1,0]
	s_branch .LBB0_474

; DI f32x16 mfma32(bf16x8 a, bf16x8 b, f32x16 c) { return __builtin_amdgcn_mfma_f32_32x32x16_bf16(a, b, c, 0, 0, 0); }
; template <int NB>
; DI void softmax_pv(f32x16 (&s)[2], float& mrun, float& lsum, f32x16 (&O)[2], unsigned vaddr) {
;     ...
;   if (NB == 2) {
; #pragma unroll
;     for (int kb = 0; kb < 2; ++kb) {
; #pragma unroll
;       for (int e = 0; e < 16; e += 2) {
;         f32x2 t = {s[kb][e], s[kb][e + 1]};
;         t = t * l2e2 - mb2;
;         f32x2 pv;
;         pv[0] = __builtin_amdgcn_exp2f(t[0]);
;         pv[1] = __builtin_amdgcn_exp2f(t[1]);
;         s[kb][e] = pv[0];
;         s[kb][e + 1] = pv[1];
;         ps2 += pv;
;       }
;       u32x4 pp[2];
; #pragma unroll
;       for (int st = 0; st < 2; ++st)
; #pragma unroll
;         for (int j = 0; j < 4; ++j) pp[st][j] = pk_bf16(s[kb][8 * st + 2 * j], s[kb][8 * st + 2 * j + 1]);
;       __builtin_amdgcn_sched_barrier(0);
;       __builtin_amdgcn_s_setprio(1);
; #pragma unroll
;       for (int st = 0; st < 2; ++st) {
;         const bf16x8 pf = as_bf16x8(pp[st]);
; #pragma unroll
;         for (int db = 0; db < 2; ++db) {
;           const int ix = ((kb * 2 + st) * 2 + db) * 2;
;           u32x4 av;
;           av[0] = vf[ix][0]; av[1] = vf[ix][1]; av[2] = vf[ix + 1][0]; av[3] = vf[ix + 1][1];
;           O[db] = mfma32(as_bf16x8(av), pf, O[db]);
;         }
;       }
;       __builtin_amdgcn_s_setprio(0);
;       __builtin_amdgcn_sched_barrier(0);
;     }
;     ...
;   lsum = lsum * alpha + (ps2[0] + ps2[1]);
.LBB0_474:
	v_mul_f32_e32 v226, 0x3fb8aa3b, v224
	v_fma_f32 v112, v112, s28, -v226
	v_fma_f32 v113, v113, s28, -v226
	s_nop 0
	v_exp_f32_e32 v228, v112
	v_exp_f32_e32 v229, v113
	v_fma_f32 v112, v114, s28, -v226
	v_fma_f32 v113, v115, s28, -v226
	s_nop 0
	v_exp_f32_e32 v230, v112
	v_exp_f32_e32 v231, v113
	v_fma_f32 v112, v116, s28, -v226
	v_fma_f32 v113, v117, s28, -v226
	s_nop 0
	v_exp_f32_e32 v232, v112
	v_exp_f32_e32 v233, v113
	v_fma_f32 v112, v118, s28, -v226
	v_fma_f32 v113, v119, s28, -v226
	v_cvt_pk_bf16_f32 v114, v232, v233
	v_exp_f32_e32 v238, v112
	v_exp_f32_e32 v239, v113
	v_fma_f32 v112, v120, s28, -v226
	v_fma_f32 v113, v121, s28, -v226
	v_cvt_pk_bf16_f32 v115, v238, v239
	v_exp_f32_e32 v120, v112
	v_exp_f32_e32 v121, v113
	v_fma_f32 v112, v122, s28, -v226
	v_fma_f32 v113, v123, s28, -v226
	v_cvt_pk_bf16_f32 v116, v120, v121
	v_exp_f32_e32 v122, v112
	v_exp_f32_e32 v123, v113
	v_fma_f32 v112, v124, s28, -v226
	v_fma_f32 v113, v125, s28, -v226
	v_cvt_pk_bf16_f32 v117, v122, v123
	v_exp_f32_e32 v124, v112
	v_exp_f32_e32 v125, v113
	v_fma_f32 v112, v126, s28, -v226
	v_fma_f32 v113, v127, s28, -v226
	v_cvt_pk_bf16_f32 v118, v124, v125
	v_exp_f32_e32 v126, v112
	v_exp_f32_e32 v127, v113
	v_cvt_pk_bf16_f32 v112, v228, v229
	v_cvt_pk_bf16_f32 v113, v230, v231
	v_cvt_pk_bf16_f32 v119, v126, v127
	s_nop 0
	v_mfma_f32_32x32x16_bf16 v[64:79], v[168:171], v[112:115], v[64:79]
	v_mfma_f32_32x32x16_bf16 v[80:95], v[164:167], v[112:115], v[80:95]
	v_add_f32_e64 v112, v228, 0
	v_add_f32_e64 v113, v229, 0
	v_add_f32_e64 v112, v230, v112
	v_add_f32_e64 v113, v231, v113
	v_add_f32_e64 v112, v232, v112
	v_add_f32_e64 v113, v233, v113
	v_pk_add_f32 v[112:113], v[238:239], v[112:113]
	v_mfma_f32_32x32x16_bf16 v[64:79], v[160:163], v[116:119], v[64:79]
	v_add_f32_e64 v112, v120, v112
	v_add_f32_e64 v113, v121, v113
	v_add_f32_e64 v112, v122, v112
	v_add_f32_e64 v113, v123, v113
	v_add_f32_e64 v112, v124, v112
	v_add_f32_e64 v113, v125, v113
	v_pk_add_f32 v[112:113], v[126:127], v[112:113]
	v_mfma_f32_32x32x16_bf16 v[80:95], v[156:159], v[116:119], v[80:95]
	s_nop 0
	v_fma_f32 v96, v96, s28, -v226
	v_fma_f32 v97, v97, s28, -v226
	v_exp_f32_e32 v114, v96
	v_exp_f32_e32 v115, v97
	v_fma_f32 v96, v98, s28, -v226
	v_fma_f32 v97, v99, s28, -v226
	s_nop 0
	v_exp_f32_e32 v116, v96
	v_exp_f32_e32 v117, v97
	v_fma_f32 v96, v100, s28, -v226
	v_fma_f32 v97, v101, s28, -v226
	s_nop 0
	v_exp_f32_e32 v118, v96
	v_exp_f32_e32 v119, v97
	v_fma_f32 v96, v102, s28, -v226
	v_fma_f32 v97, v103, s28, -v226
	v_cvt_pk_bf16_f32 v98, v118, v119
	v_exp_f32_e32 v120, v96
	v_exp_f32_e32 v121, v97
	v_fma_f32 v96, v104, s28, -v226
	v_fma_f32 v97, v105, s28, -v226
	v_cvt_pk_bf16_f32 v99, v120, v121
	v_exp_f32_e32 v104, v96
	v_exp_f32_e32 v105, v97
	v_fma_f32 v96, v106, s28, -v226
	v_fma_f32 v97, v107, s28, -v226
	v_cvt_pk_bf16_f32 v100, v104, v105
	v_exp_f32_e32 v106, v96
	v_exp_f32_e32 v107, v97
	v_fma_f32 v96, v108, s28, -v226
	v_fma_f32 v97, v109, s28, -v226
	v_cvt_pk_bf16_f32 v101, v106, v107
	v_exp_f32_e32 v108, v96
	v_exp_f32_e32 v109, v97
	v_fma_f32 v96, v110, s28, -v226
	v_fma_f32 v97, v111, s28, -v226
	v_cvt_pk_bf16_f32 v102, v108, v109
	v_exp_f32_e32 v110, v96
	v_exp_f32_e32 v111, v97
	v_cvt_pk_bf16_f32 v96, v114, v115
	v_cvt_pk_bf16_f32 v97, v116, v117
	v_cvt_pk_bf16_f32 v103, v110, v111
	s_nop 0
	v_mfma_f32_32x32x16_bf16 v[64:79], v[152:155], v[96:99], v[64:79]
	v_mfma_f32_32x32x16_bf16 v[80:95], v[10:13], v[96:99], v[80:95]
	v_mfma_f32_32x32x16_bf16 v[64:79], v[6:9], v[100:103], v[64:79]
	v_add_f32_e64 v6, v114, v112
	v_add_f32_e64 v7, v115, v113
	v_add_f32_e64 v6, v116, v6
	v_add_f32_e64 v7, v117, v7
	v_add_f32_e64 v6, v118, v6
	v_add_f32_e64 v7, v119, v7
	v_pk_add_f32 v[6:7], v[120:121], v[6:7]
	v_mfma_f32_32x32x16_bf16 v[80:95], v[2:5], v[100:103], v[80:95]
	v_add_f32_e64 v6, v104, v6
	v_add_f32_e64 v7, v105, v7
	v_add_f32_e64 v6, v106, v6
	v_add_f32_e64 v7, v107, v7
	v_add_f32_e64 v6, v108, v6
	v_add_f32_e64 v7, v109, v7
	v_pk_add_f32 v[6:7], v[110:111], v[6:7]
	s_nop 0
	v_add_f32_e32 v2, v6, v7
	v_mov_b64_e32 v[126:127], v[78:79]
	s_nop 1
	v_mov_b64_e32 v[110:111], v[94:95]
	v_fmac_f32_e32 v2, v192, v0
	v_mov_b64_e32 v[124:125], v[76:77]
	v_mov_b64_e32 v[122:123], v[74:75]
	v_mov_b64_e32 v[120:121], v[72:73]
	v_mov_b64_e32 v[118:119], v[70:71]
	v_mov_b64_e32 v[116:117], v[68:69]
	v_mov_b64_e32 v[114:115], v[66:67]
	v_mov_b64_e32 v[112:113], v[64:65]
	v_mov_b64_e32 v[108:109], v[92:93]
	v_mov_b64_e32 v[106:107], v[90:91]
	v_mov_b64_e32 v[104:105], v[88:89]
	v_mov_b64_e32 v[102:103], v[86:87]
	v_mov_b64_e32 v[100:101], v[84:85]
	v_mov_b64_e32 v[98:99], v[82:83]
	v_mov_b64_e32 v[96:97], v[80:81]
	s_branch .LBB0_513

; DI f32x16 mfma32(bf16x8 a, bf16x8 b, f32x16 c) { return __builtin_amdgcn_mfma_f32_32x32x16_bf16(a, b, c, 0, 0, 0); }
; template <int NB>
; DI void softmax_pv(f32x16 (&s)[2], float& mrun, float& lsum, f32x16 (&O)[2], unsigned vaddr) {
;     ...
; #pragma unroll
;     for (int e = 0; e < 16; e += 2) {
;       f32x2 t = {s[0][e], s[0][e + 1]};
;       t = t * l2e2 - mb2;
;       f32x2 pv;
;       pv[0] = __builtin_amdgcn_exp2f(t[0]);
;       pv[1] = __builtin_amdgcn_exp2f(t[1]);
;       s[0][e] = pv[0];
;       s[0][e + 1] = pv[1];
;       ps2 += pv;
;     }
;     __builtin_amdgcn_s_setprio(1);
; #pragma unroll
;     for (int st = 0; st < 2; ++st) {
;       u32x4 pp;
; #pragma unroll
;       for (int j = 0; j < 4; ++j) pp[j] = pk_bf16(s[0][8 * st + 2 * j], s[0][8 * st + 2 * j + 1]);
;       const bf16x8 pf = as_bf16x8(pp);
; #pragma unroll
;       for (int db = 0; db < 2; ++db) {
;         const int ix = (st * 2 + db) * 2;
;         u32x4 av;
;         av[0] = vf8[ix][0]; av[1] = vf8[ix][1]; av[2] = vf8[ix + 1][0]; av[3] = vf8[ix + 1][1];
;         O[db] = mfma32(as_bf16x8(av), pf, O[db]);
;       }
;     }
;     __builtin_amdgcn_s_setprio(0);
;   }
;   lsum = lsum * alpha + (ps2[0] + ps2[1]);
.LBB0_511:
	v_mul_f32_e32 v78, 0x3fb8aa3b, v193
	v_fma_f32 v14, v14, s28, -v78
	v_fma_f32 v15, v15, s28, -v78
	v_fma_f32 v68, v68, s28, -v78
	v_fma_f32 v69, v69, s28, -v78
	v_exp_f32_e32 v14, v14
	v_exp_f32_e32 v15, v15
	v_exp_f32_e32 v84, v68
	v_exp_f32_e32 v85, v69
	v_fma_f32 v68, v70, s28, -v78
	v_fma_f32 v69, v71, s28, -v78
	v_fma_f32 v80, v80, s28, -v78
	v_fma_f32 v81, v81, s28, -v78
	v_exp_f32_e32 v86, v68
	v_exp_f32_e32 v87, v69
	v_fma_f32 v68, v72, s28, -v78
	v_fma_f32 v69, v73, s28, -v78
	v_fma_f32 v82, v82, s28, -v78
	v_fma_f32 v83, v83, s28, -v78
	v_exp_f32_e32 v72, v68
	v_exp_f32_e32 v73, v69
	v_fma_f32 v68, v74, s28, -v78
	v_fma_f32 v69, v75, s28, -v78
	v_exp_f32_e32 v80, v80
	v_exp_f32_e32 v74, v68
	v_exp_f32_e32 v75, v69
	v_fma_f32 v68, v76, s28, -v78
	v_fma_f32 v69, v77, s28, -v78
	v_exp_f32_e32 v81, v81
	v_exp_f32_e32 v82, v82
	v_exp_f32_e32 v83, v83
	v_exp_f32_e32 v76, v68
	v_exp_f32_e32 v77, v69
	s_nop 0
	v_cvt_pk_bf16_f32 v68, v14, v15
	v_cvt_pk_bf16_f32 v69, v80, v81
	v_cvt_pk_bf16_f32 v70, v82, v83
	v_cvt_pk_bf16_f32 v71, v84, v85
	s_nop 1
	v_mfma_f32_32x32x16_bf16 v[32:47], v[64:67], v[68:71], v[32:47]
	v_mfma_f32_32x32x16_bf16 v[48:63], v[10:13], v[68:71], v[48:63]
	v_cvt_pk_bf16_f32 v10, v86, v87
	v_cvt_pk_bf16_f32 v11, v72, v73
	v_cvt_pk_bf16_f32 v12, v74, v75
	v_cvt_pk_bf16_f32 v13, v76, v77
	s_nop 1
	v_mfma_f32_32x32x16_bf16 v[32:47], v[6:9], v[10:13], v[32:47]
	v_add_f32_e64 v6, v14, 0
	v_add_f32_e64 v7, v15, 0
	v_add_f32_e64 v6, v80, v6
	v_add_f32_e64 v7, v81, v7
	v_add_f32_e64 v6, v82, v6
	v_add_f32_e64 v7, v83, v7
	v_pk_add_f32 v[6:7], v[84:85], v[6:7]
	v_mfma_f32_32x32x16_bf16 v[48:63], v[2:5], v[10:13], v[48:63]
	v_add_f32_e64 v6, v86, v6
	v_add_f32_e64 v7, v87, v7
	v_add_f32_e64 v6, v72, v6
	v_add_f32_e64 v7, v73, v7
	v_add_f32_e64 v6, v74, v6
	v_add_f32_e64 v7, v75, v7
	v_pk_add_f32 v[6:7], v[76:77], v[6:7]
	s_nop 0
	v_add_f32_e32 v2, v6, v7
	v_fmac_f32_e32 v2, v192, v0
	v_mov_b32_e32 v223, v47
	v_mov_b32_e32 v222, v46
	v_mov_b32_e32 v221, v45
	v_mov_b32_e32 v220, v44
	v_mov_b32_e32 v219, v43
	v_mov_b32_e32 v218, v42
	v_mov_b32_e32 v217, v41
	v_mov_b32_e32 v216, v40
	v_mov_b32_e32 v215, v39
	v_mov_b32_e32 v214, v38
	v_mov_b32_e32 v213, v37
	v_mov_b32_e32 v212, v36
	v_mov_b32_e32 v211, v35
	v_mov_b32_e32 v210, v34
	v_mov_b32_e32 v209, v33
	v_mov_b32_e32 v208, v32
	v_mov_b32_e32 v207, v63
	v_mov_b32_e32 v206, v62
	v_mov_b32_e32 v205, v61
	v_mov_b32_e32 v204, v60
	v_mov_b32_e32 v203, v59
	v_mov_b32_e32 v202, v58
	v_mov_b32_e32 v201, v57
	v_mov_b32_e32 v200, v56
	v_mov_b32_e32 v199, v55
	v_mov_b32_e32 v198, v54
	v_mov_b32_e32 v197, v53
	v_mov_b32_e32 v196, v52
	v_mov_b32_e32 v195, v51
	v_mov_b32_e32 v194, v50
	v_mov_b32_e32 v15, v49
	v_mov_b32_e32 v14, v48
	v_mov_b32_e32 v192, v2
